# GEMM K-loop header placed at byte offset 24 mod 64 (alignment sweep: 0/8/16/20/24/28/32/40/48/56 gave 3832/3859/3833/3857/3748/3866/3798/3827/3829/3867 us)
# baseline (speedup 1.0000x reference)
; #define PG8_STAGE(bufoff, gbase, voff) do { _Pragma("unroll") for (int _i = 0; _i < 2; ++_i) \
;         __builtin_amdgcn_global_load_lds((const unsigned*)((const char*)(gbase) + (voff)[_i]), (LAS unsigned*)(lds + (bufoff) + ldsw + _i * 8192), 16, 0, 0); } while (0)
; #define PG8_LDA(dst, b, h) do { _Pragma("unroll") for (int m = 0; m < 4; ++m) _Pragma("unroll") for (int k = 0; k < 2; ++k) dst[m][k] = *(const LAS bf16x8*)(lds + PG8_SA(b, h) + aoff + m * 2048 + k * 1024); } while (0)
; #define PG8_LDB(dst, b, h) do { _Pragma("unroll") for (int n = 0; n < 2; ++n) _Pragma("unroll") for (int k = 0; k < 2; ++k) dst[n][k] = *(const LAS bf16x8*)(lds + PG8_SB(b, h) + boff + n * 2048 + k * 1024); } while (0)
; #define PG8_MMA(ai, bj, At, Bt) do { __builtin_amdgcn_s_setprio(1); _Pragma("unroll") for (int m = 0; m < 4; ++m) _Pragma("unroll") for (int n = 0; n < 2; ++n) _Pragma("unroll") for (int k = 0; k < 2; ++k) \
;         acc[ai][bj][m][n] = __builtin_amdgcn_mfma_f32_16x16x32_bf16(Bt[n][k], At[m][k], acc[ai][bj][m][n], 0, 0, 0); __builtin_amdgcn_s_setprio(0); } while (0)
; #define PG8_WAIT_V(n) asm volatile("s_waitcnt vmcnt(" #n ")" ::: "memory")
; #define PG8_WAIT_L(n) asm volatile("s_waitcnt lgkmcnt(" #n ")" ::: "memory")
; #define PG8_BAR __builtin_amdgcn_s_barrier()
; #define PG8_SCHED __builtin_amdgcn_sched_barrier(0)
; __device__ __forceinline__ void gemm_phase(LAS unsigned char* lds, const LAS unsigned char* jt, const int K, const int n0, const int n1, const int G, const int c) {
;     ...
;         for (int t = 0; t < nt; t += 2) {
;             const bool last = (t == nt - 2);
;             const char* a1 = cA + (size_t)(t + 1) * kstep;
;             const char* a2 = last ? nA : cA + (size_t)(t + 2) * kstep; const char* b2 = last ? nB : cB + (size_t)(t + 2) * kstep;
;             const char* a3 = a2 + kstep; const char* b3 = b2 + kstep;
;             PG8_LDB(B0, 0, 0); PG8_LDB(B1, 0, 1); PG8_SCHED; PG8_LDA(At, 0, 0); PG8_STAGE(PG8_SA(1, 1), a1 + hstep, voffA);
;             PG8_WAIT_V(8); PG8_WAIT_L(0); PG8_BAR; PG8_MMA(0, 0, At, B0); PG8_MMA(0, 1, At, B1); PG8_BAR; PG8_SCHED;
.LBB0_293:
	s_andn2_b64 vcc, exec, s[28:29]
	s_cbranch_vccnz .LBB0_301
	s_add_u32 s14, s0, 0x100
	s_addc_u32 s15, s1, 0
	s_add_u32 s0, s12, 0x80
	v_mov_b32_e32 v0, 0
	s_addc_u32 s1, s13, 0
	s_mov_b32 s12, 0
	v_mov_b32_e32 v1, v0
	v_mov_b32_e32 v2, v0
	v_mov_b32_e32 v3, v0
	v_mov_b32_e32 v4, v0
	v_mov_b32_e32 v5, v0
	v_mov_b32_e32 v6, v0
	v_mov_b32_e32 v7, v0
	v_mov_b32_e32 v16, v0
	v_mov_b32_e32 v17, v0
	v_mov_b32_e32 v18, v0
	v_mov_b32_e32 v19, v0
	v_mov_b32_e32 v20, v0
	v_mov_b32_e32 v21, v0
	v_mov_b32_e32 v22, v0
	v_mov_b32_e32 v23, v0
	v_mov_b32_e32 v32, v0
	v_mov_b32_e32 v33, v0
	v_mov_b32_e32 v34, v0
	v_mov_b32_e32 v35, v0
	v_mov_b32_e32 v36, v0
	v_mov_b32_e32 v37, v0
	v_mov_b32_e32 v38, v0
	v_mov_b32_e32 v39, v0
	v_mov_b32_e32 v48, v0
	v_mov_b32_e32 v49, v0
	v_mov_b32_e32 v50, v0
	v_mov_b32_e32 v51, v0
	v_mov_b32_e32 v52, v0
	v_mov_b32_e32 v53, v0
	v_mov_b32_e32 v54, v0
	v_mov_b32_e32 v55, v0
	v_mov_b32_e32 v8, v0
	v_mov_b32_e32 v9, v0
	v_mov_b32_e32 v10, v0
	v_mov_b32_e32 v11, v0
	v_mov_b32_e32 v12, v0
	v_mov_b32_e32 v13, v0
	v_mov_b32_e32 v14, v0
	v_mov_b32_e32 v15, v0
	v_mov_b32_e32 v24, v0
	v_mov_b32_e32 v25, v0
	v_mov_b32_e32 v26, v0
	v_mov_b32_e32 v27, v0
	v_mov_b32_e32 v28, v0
	v_mov_b32_e32 v29, v0
	v_mov_b32_e32 v30, v0
	v_mov_b32_e32 v31, v0
	v_mov_b32_e32 v40, v0
	v_mov_b32_e32 v41, v0
	v_mov_b32_e32 v42, v0
	v_mov_b32_e32 v43, v0
	v_mov_b32_e32 v44, v0
	v_mov_b32_e32 v45, v0
	v_mov_b32_e32 v46, v0
	v_mov_b32_e32 v47, v0
	v_mov_b32_e32 v56, v0
	v_mov_b32_e32 v57, v0
	v_mov_b32_e32 v58, v0
	v_mov_b32_e32 v59, v0
	v_mov_b32_e32 v60, v0
	v_mov_b32_e32 v61, v0
	v_mov_b32_e32 v62, v0
	v_mov_b32_e32 v63, v0
	v_mov_b32_e32 v64, v0
	v_mov_b32_e32 v65, v0
	v_mov_b32_e32 v66, v0
	v_mov_b32_e32 v67, v0
	v_mov_b32_e32 v68, v0
	v_mov_b32_e32 v69, v0
	v_mov_b32_e32 v70, v0
	v_mov_b32_e32 v71, v0
	v_mov_b32_e32 v80, v0
	v_mov_b32_e32 v81, v0
	v_mov_b32_e32 v82, v0
	v_mov_b32_e32 v83, v0
	v_mov_b32_e32 v84, v0
	v_mov_b32_e32 v85, v0
	v_mov_b32_e32 v86, v0
	v_mov_b32_e32 v87, v0
	v_mov_b32_e32 v100, v0
	v_mov_b32_e32 v101, v0
	v_mov_b32_e32 v102, v0
	v_mov_b32_e32 v103, v0
	v_mov_b32_e32 v104, v0
	v_mov_b32_e32 v105, v0
	v_mov_b32_e32 v106, v0
	v_mov_b32_e32 v107, v0
	v_mov_b32_e32 v116, v0
	v_mov_b32_e32 v117, v0
	v_mov_b32_e32 v118, v0
	v_mov_b32_e32 v119, v0
	v_mov_b32_e32 v120, v0
	v_mov_b32_e32 v121, v0
	v_mov_b32_e32 v122, v0
	v_mov_b32_e32 v123, v0
	v_mov_b32_e32 v72, v0
	v_mov_b32_e32 v73, v0
	v_mov_b32_e32 v74, v0
	v_mov_b32_e32 v75, v0
	v_mov_b32_e32 v76, v0
	v_mov_b32_e32 v77, v0
	v_mov_b32_e32 v78, v0
	v_mov_b32_e32 v79, v0
	v_mov_b32_e32 v88, v0
	v_mov_b32_e32 v89, v0
	v_mov_b32_e32 v90, v0
	v_mov_b32_e32 v91, v0
	v_mov_b32_e32 v92, v0
	v_mov_b32_e32 v93, v0
	v_mov_b32_e32 v94, v0
	v_mov_b32_e32 v95, v0
	v_mov_b32_e32 v108, v0
	v_mov_b32_e32 v109, v0
	v_mov_b32_e32 v110, v0
	v_mov_b32_e32 v111, v0
	v_mov_b32_e32 v112, v0
	v_mov_b32_e32 v113, v0
	v_mov_b32_e32 v114, v0
	v_mov_b32_e32 v115, v0
	v_mov_b32_e32 v124, v0
	v_mov_b32_e32 v125, v0
	v_mov_b32_e32 v126, v0
	v_mov_b32_e32 v127, v0
	v_mov_b32_e32 v128, v0
	v_mov_b32_e32 v129, v0
	v_mov_b32_e32 v130, v0
	v_mov_b32_e32 v131, v0
	.p2align 6
	s_nop 0
	s_nop 0
	s_nop 0
	s_nop 0
	s_nop 0
	s_nop 0
.LBB0_295:
	s_add_i32 s18, s12, 2
	s_add_u32 s19, s0, 0x80
	s_addc_u32 s13, s1, 0
	s_add_i32 s26, 0, 0x10000
	s_cmp_eq_u32 s54, s12
	s_cselect_b32 s13, s41, s13
	s_cselect_b32 s12, s40, s19
	v_add_u32_e32 v96, s26, v189
	s_cselect_b32 s25, s43, s15
	s_cselect_b32 s24, s42, s14
	s_add_i32 s19, 0, 0x14000
	ds_read_b128 v[134:137], v96
	ds_read_b128 v[138:141], v96 offset:1024
	ds_read_b128 v[142:145], v96 offset:2048
	ds_read_b128 v[160:163], v96 offset:3072
	v_add_u32_e32 v96, s19, v189
	ds_read_b128 v[164:167], v96
	ds_read_b128 v[168:171], v96 offset:1024
	ds_read_b128 v[172:175], v96 offset:2048
	ds_read_b128 v[176:179], v96 offset:3072
	v_lshl_add_u64 v[98:99], s[0:1], 0, v[158:159]
	s_add_i32 m0, s45, 0xc000
	ds_read_b128 v[180:183], v190
	ds_read_b128 v[198:201], v190 offset:1024
	ds_read_b128 v[204:207], v190 offset:2048
	ds_read_b128 v[226:229], v190 offset:3072
	ds_read_b128 v[230:233], v190 offset:4096
	ds_read_b128 v[234:237], v190 offset:5120
	ds_read_b128 v[238:241], v190 offset:6144
	ds_read_b128 v[242:245], v190 offset:7168
	global_load_lds_dwordx4 v[98:99], off
	v_lshl_add_u64 v[98:99], s[0:1], 0, v[156:157]
	s_add_i32 m0, s45, 0xe000
	s_nop 0
	global_load_lds_dwordx4 v[98:99], off
	s_waitcnt vmcnt(8)
	s_waitcnt lgkmcnt(0)
	s_barrier
; #define PG8_STAGE(bufoff, gbase, voff) do { _Pragma("unroll") for (int _i = 0; _i < 2; ++_i) \
;         __builtin_amdgcn_global_load_lds((const unsigned*)((const char*)(gbase) + (voff)[_i]), (LAS unsigned*)(lds + (bufoff) + ldsw + _i * 8192), 16, 0, 0); } while (0)
; #define PG8_LDA(dst, b, h) do { _Pragma("unroll") for (int m = 0; m < 4; ++m) _Pragma("unroll") for (int k = 0; k < 2; ++k) dst[m][k] = *(const LAS bf16x8*)(lds + PG8_SA(b, h) + aoff + m * 2048 + k * 1024); } while (0)
; #define PG8_MMA(ai, bj, At, Bt) do { __builtin_amdgcn_s_setprio(1); _Pragma("unroll") for (int m = 0; m < 4; ++m) _Pragma("unroll") for (int n = 0; n < 2; ++n) _Pragma("unroll") for (int k = 0; k < 2; ++k) \
;         acc[ai][bj][m][n] = __builtin_amdgcn_mfma_f32_16x16x32_bf16(Bt[n][k], At[m][k], acc[ai][bj][m][n], 0, 0, 0); __builtin_amdgcn_s_setprio(0); } while (0)
; #define PG8_WAIT_V(n) asm volatile("s_waitcnt vmcnt(" #n ")" ::: "memory")
; #define PG8_WAIT_L(n) asm volatile("s_waitcnt lgkmcnt(" #n ")" ::: "memory")
; #define PG8_BAR __builtin_amdgcn_s_barrier()
; #define PG8_SCHED __builtin_amdgcn_sched_barrier(0)
; __device__ __forceinline__ void gemm_phase(LAS unsigned char* lds, const LAS unsigned char* jt, const int K, const int n0, const int n1, const int G, const int c) {
;     ...
;             PG8_WAIT_V(8); PG8_WAIT_L(0); PG8_BAR; PG8_MMA(0, 0, At, B0); PG8_MMA(0, 1, At, B1); PG8_BAR; PG8_SCHED;
;             PG8_LDA(At, 0, 1); PG8_STAGE(PG8_SB(0, 0), b2, voffB); PG8_STAGE(PG8_SB(0, 1), b2 + hstep, voffB); PG8_STAGE(PG8_SA(0, 0), a2, voffA);
;             PG8_WAIT_V(8); PG8_WAIT_L(0); PG8_BAR; PG8_MMA(1, 0, At, B0); PG8_MMA(1, 1, At, B1); PG8_BAR; PG8_SCHED;
	s_setprio 1
	s_waitcnt lgkmcnt(0)
	v_mfma_f32_16x16x32_bf16 v[128:131], v[134:137], v[180:183], v[128:131]
	v_mfma_f32_16x16x32_bf16 v[124:127], v[142:145], v[180:183], v[124:127]
	v_mfma_f32_16x16x32_bf16 v[112:115], v[134:137], v[204:207], v[112:115]
	v_mfma_f32_16x16x32_bf16 v[108:111], v[142:145], v[204:207], v[108:111]
	v_mfma_f32_16x16x32_bf16 v[92:95], v[134:137], v[230:233], v[92:95]
	v_mfma_f32_16x16x32_bf16 v[88:91], v[142:145], v[230:233], v[88:91]
	v_mfma_f32_16x16x32_bf16 v[76:79], v[134:137], v[238:241], v[76:79]
	v_mfma_f32_16x16x32_bf16 v[72:75], v[142:145], v[238:241], v[72:75]
	v_mfma_f32_16x16x32_bf16 v[128:131], v[138:141], v[198:201], v[128:131]
	v_mfma_f32_16x16x32_bf16 v[124:127], v[160:163], v[198:201], v[124:127]
	v_mfma_f32_16x16x32_bf16 v[112:115], v[138:141], v[226:229], v[112:115]
	v_mfma_f32_16x16x32_bf16 v[108:111], v[160:163], v[226:229], v[108:111]
	v_mfma_f32_16x16x32_bf16 v[92:95], v[138:141], v[234:237], v[92:95]
	v_mfma_f32_16x16x32_bf16 v[88:91], v[160:163], v[234:237], v[88:91]
	v_mfma_f32_16x16x32_bf16 v[76:79], v[138:141], v[242:245], v[76:79]
	v_mfma_f32_16x16x32_bf16 v[72:75], v[160:163], v[242:245], v[72:75]
	s_setprio 0
	s_setprio 1
	v_mfma_f32_16x16x32_bf16 v[120:123], v[164:167], v[180:183], v[120:123]
	v_mfma_f32_16x16x32_bf16 v[116:119], v[172:175], v[180:183], v[116:119]
	v_mfma_f32_16x16x32_bf16 v[104:107], v[164:167], v[204:207], v[104:107]
	v_mfma_f32_16x16x32_bf16 v[98:101], v[172:175], v[204:207], v[100:103]
	v_mfma_f32_16x16x32_bf16 v[84:87], v[164:167], v[230:233], v[84:87]
	v_mfma_f32_16x16x32_bf16 v[80:83], v[172:175], v[230:233], v[80:83]
	v_mfma_f32_16x16x32_bf16 v[68:71], v[164:167], v[238:241], v[68:71]
	v_mfma_f32_16x16x32_bf16 v[64:67], v[172:175], v[238:241], v[64:67]
	v_mfma_f32_16x16x32_bf16 v[120:123], v[168:171], v[198:201], v[120:123]
	v_mfma_f32_16x16x32_bf16 v[116:119], v[176:179], v[198:201], v[116:119]
	v_mfma_f32_16x16x32_bf16 v[104:107], v[168:171], v[226:229], v[104:107]
	v_mfma_f32_16x16x32_bf16 v[98:101], v[176:179], v[226:229], v[98:101]
	v_mfma_f32_16x16x32_bf16 v[84:87], v[168:171], v[234:237], v[84:87]
	v_mfma_f32_16x16x32_bf16 v[80:83], v[176:179], v[234:237], v[80:83]
	v_mfma_f32_16x16x32_bf16 v[68:71], v[168:171], v[242:245], v[68:71]
	v_mfma_f32_16x16x32_bf16 v[64:67], v[176:179], v[242:245], v[64:67]
	s_setprio 0
	s_barrier
	s_add_i32 s26, s26, s44
	v_lshl_add_u64 v[146:147], s[24:25], 0, v[150:151]
	s_mov_b32 m0, s26
	ds_read_b128 v[180:183], v190 offset:16384
	ds_read_b128 v[198:201], v190 offset:17408
	ds_read_b128 v[204:207], v190 offset:18432
	ds_read_b128 v[226:229], v190 offset:19456
	ds_read_b128 v[230:233], v190 offset:20480
	ds_read_b128 v[234:237], v190 offset:21504
	ds_read_b128 v[238:241], v190 offset:22528
	ds_read_b128 v[242:245], v190 offset:23552
	global_load_lds_dwordx4 v[146:147], off
	s_add_i32 m0, s26, 0x2000
	v_lshl_add_u64 v[184:185], s[24:25], 0, v[154:155]
	s_add_u32 s24, s24, s4
	s_addc_u32 s25, s25, s5
	s_add_i32 s19, s19, s44
	global_load_lds_dwordx4 v[184:185], off
	v_lshl_add_u64 v[192:193], s[24:25], 0, v[150:151]
	s_mov_b32 m0, s19
	v_lshl_add_u64 v[208:209], s[24:25], 0, v[154:155]
	global_load_lds_dwordx4 v[192:193], off
	s_add_i32 m0, s19, 0x2000
	v_lshl_add_u64 v[246:247], s[12:13], 0, v[148:149]
	global_load_lds_dwordx4 v[208:209], off
	s_mov_b32 m0, s45
	v_lshl_add_u64 v[248:249], s[12:13], 0, v[152:153]
	global_load_lds_dwordx4 v[246:247], off
	s_mov_b32 m0, s46
	s_nop 0
	global_load_lds_dwordx4 v[248:249], off
	s_waitcnt vmcnt(8)
	s_waitcnt lgkmcnt(0)
	s_barrier
	s_setprio 1
	s_waitcnt lgkmcnt(0)
	v_mfma_f32_16x16x32_bf16 v[60:63], v[134:137], v[180:183], v[60:63]
	v_mfma_f32_16x16x32_bf16 v[56:59], v[142:145], v[180:183], v[56:59]
	v_mfma_f32_16x16x32_bf16 v[44:47], v[134:137], v[204:207], v[44:47]
	v_mfma_f32_16x16x32_bf16 v[40:43], v[142:145], v[204:207], v[40:43]
	v_mfma_f32_16x16x32_bf16 v[28:31], v[134:137], v[230:233], v[28:31]
	v_mfma_f32_16x16x32_bf16 v[24:27], v[142:145], v[230:233], v[24:27]
	v_mfma_f32_16x16x32_bf16 v[12:15], v[134:137], v[238:241], v[12:15]
	v_mfma_f32_16x16x32_bf16 v[8:11], v[142:145], v[238:241], v[8:11]
	v_mfma_f32_16x16x32_bf16 v[60:63], v[138:141], v[198:201], v[60:63]
	v_mfma_f32_16x16x32_bf16 v[56:59], v[160:163], v[198:201], v[56:59]
	v_mfma_f32_16x16x32_bf16 v[44:47], v[138:141], v[226:229], v[44:47]
	v_mfma_f32_16x16x32_bf16 v[40:43], v[160:163], v[226:229], v[40:43]
	v_mfma_f32_16x16x32_bf16 v[28:31], v[138:141], v[234:237], v[28:31]
	v_mfma_f32_16x16x32_bf16 v[24:27], v[160:163], v[234:237], v[24:27]
	v_mfma_f32_16x16x32_bf16 v[12:15], v[138:141], v[242:245], v[12:15]
	v_mfma_f32_16x16x32_bf16 v[8:11], v[160:163], v[242:245], v[8:11]
	s_setprio 0
	s_setprio 1
	v_mfma_f32_16x16x32_bf16 v[52:55], v[164:167], v[180:183], v[52:55]
	v_mfma_f32_16x16x32_bf16 v[48:51], v[172:175], v[180:183], v[48:51]
	v_mfma_f32_16x16x32_bf16 v[36:39], v[164:167], v[204:207], v[36:39]
	v_mfma_f32_16x16x32_bf16 v[32:35], v[172:175], v[204:207], v[32:35]
	v_mfma_f32_16x16x32_bf16 v[20:23], v[164:167], v[230:233], v[20:23]
	v_mfma_f32_16x16x32_bf16 v[16:19], v[172:175], v[230:233], v[16:19]
	v_mfma_f32_16x16x32_bf16 v[4:7], v[164:167], v[238:241], v[4:7]
	v_mfma_f32_16x16x32_bf16 v[0:3], v[172:175], v[238:241], v[0:3]
	v_mfma_f32_16x16x32_bf16 v[52:55], v[168:171], v[198:201], v[52:55]
	v_mfma_f32_16x16x32_bf16 v[48:51], v[176:179], v[198:201], v[48:51]
	v_mfma_f32_16x16x32_bf16 v[36:39], v[168:171], v[226:229], v[36:39]
	v_mfma_f32_16x16x32_bf16 v[32:35], v[176:179], v[226:229], v[32:35]
	v_mfma_f32_16x16x32_bf16 v[20:23], v[168:171], v[234:237], v[20:23]
	v_mfma_f32_16x16x32_bf16 v[16:19], v[176:179], v[234:237], v[16:19]
	v_mfma_f32_16x16x32_bf16 v[4:7], v[168:171], v[242:245], v[4:7]
	v_mfma_f32_16x16x32_bf16 v[0:3], v[176:179], v[242:245], v[0:3]
	s_setprio 0
	s_barrier
; #define PG8_STAGE(bufoff, gbase, voff) do { _Pragma("unroll") for (int _i = 0; _i < 2; ++_i) \
;         __builtin_amdgcn_global_load_lds((const unsigned*)((const char*)(gbase) + (voff)[_i]), (LAS unsigned*)(lds + (bufoff) + ldsw + _i * 8192), 16, 0, 0); } while (0)
; #define PG8_LDA(dst, b, h) do { _Pragma("unroll") for (int m = 0; m < 4; ++m) _Pragma("unroll") for (int k = 0; k < 2; ++k) dst[m][k] = *(const LAS bf16x8*)(lds + PG8_SA(b, h) + aoff + m * 2048 + k * 1024); } while (0)
; #define PG8_LDB(dst, b, h) do { _Pragma("unroll") for (int n = 0; n < 2; ++n) _Pragma("unroll") for (int k = 0; k < 2; ++k) dst[n][k] = *(const LAS bf16x8*)(lds + PG8_SB(b, h) + boff + n * 2048 + k * 1024); } while (0)
; #define PG8_MMA(ai, bj, At, Bt) do { __builtin_amdgcn_s_setprio(1); _Pragma("unroll") for (int m = 0; m < 4; ++m) _Pragma("unroll") for (int n = 0; n < 2; ++n) _Pragma("unroll") for (int k = 0; k < 2; ++k) \
;         acc[ai][bj][m][n] = __builtin_amdgcn_mfma_f32_16x16x32_bf16(Bt[n][k], At[m][k], acc[ai][bj][m][n], 0, 0, 0); __builtin_amdgcn_s_setprio(0); } while (0)
; #define PG8_WAIT_V(n) asm volatile("s_waitcnt vmcnt(" #n ")" ::: "memory")
; #define PG8_WAIT_L(n) asm volatile("s_waitcnt lgkmcnt(" #n ")" ::: "memory")
; #define PG8_BAR __builtin_amdgcn_s_barrier()
; #define PG8_SCHED __builtin_amdgcn_sched_barrier(0)
; __device__ __forceinline__ void gemm_phase(LAS unsigned char* lds, const LAS unsigned char* jt, const int K, const int n0, const int n1, const int G, const int c) {
;     ...
;             PG8_LDB(B0, 1, 0); PG8_LDB(B1, 1, 1); PG8_SCHED; PG8_LDA(At, 1, 0); PG8_STAGE(PG8_SA(0, 1), a2 + hstep, voffA);
;             PG8_WAIT_V(8); PG8_WAIT_L(0); PG8_BAR; PG8_MMA(0, 0, At, B0); PG8_MMA(0, 1, At, B1); PG8_BAR; PG8_SCHED;
	s_add_i32 s19, 0, 0x18000
	v_add_u32_e32 v96, s19, v189
	s_add_i32 s24, 0, 0x1c000
	ds_read_b128 v[134:137], v96
	ds_read_b128 v[138:141], v96 offset:1024
	ds_read_b128 v[142:145], v96 offset:2048
	ds_read_b128 v[160:163], v96 offset:3072
	v_add_u32_e32 v96, s24, v189
	ds_read_b128 v[164:167], v96
	ds_read_b128 v[168:171], v96 offset:1024
	ds_read_b128 v[172:175], v96 offset:2048
	ds_read_b128 v[176:179], v96 offset:3072
	s_add_u32 s12, s12, s4
	s_addc_u32 s13, s13, s5
	s_mov_b32 m0, s47
	v_lshl_add_u64 v[102:103], s[12:13], 0, v[148:149]
	ds_read_b128 v[180:183], v190 offset:32768
	ds_read_b128 v[198:201], v190 offset:33792
	ds_read_b128 v[204:207], v190 offset:34816
	ds_read_b128 v[226:229], v190 offset:35840
	ds_read_b128 v[230:233], v190 offset:36864
	ds_read_b128 v[234:237], v190 offset:37888
	ds_read_b128 v[238:241], v190 offset:38912
	ds_read_b128 v[242:245], v190 offset:39936
	global_load_lds_dwordx4 v[102:103], off
	v_lshl_add_u64 v[102:103], s[12:13], 0, v[152:153]
	s_mov_b32 m0, s48
	s_nop 0
	global_load_lds_dwordx4 v[102:103], off
	s_waitcnt vmcnt(8)
	s_waitcnt lgkmcnt(0)
	s_barrier
	s_setprio 1
	s_waitcnt lgkmcnt(0)
	v_mfma_f32_16x16x32_bf16 v[128:131], v[134:137], v[180:183], v[128:131]
	v_mfma_f32_16x16x32_bf16 v[124:127], v[142:145], v[180:183], v[124:127]
	v_mfma_f32_16x16x32_bf16 v[112:115], v[134:137], v[204:207], v[112:115]
	v_mfma_f32_16x16x32_bf16 v[108:111], v[142:145], v[204:207], v[108:111]
	v_mfma_f32_16x16x32_bf16 v[92:95], v[134:137], v[230:233], v[92:95]
	v_mfma_f32_16x16x32_bf16 v[88:91], v[142:145], v[230:233], v[88:91]
	v_mfma_f32_16x16x32_bf16 v[76:79], v[134:137], v[238:241], v[76:79]
	v_mfma_f32_16x16x32_bf16 v[72:75], v[142:145], v[238:241], v[72:75]
	v_mfma_f32_16x16x32_bf16 v[128:131], v[138:141], v[198:201], v[128:131]
	v_mfma_f32_16x16x32_bf16 v[124:127], v[160:163], v[198:201], v[124:127]
	v_mfma_f32_16x16x32_bf16 v[112:115], v[138:141], v[226:229], v[112:115]
	v_mfma_f32_16x16x32_bf16 v[108:111], v[160:163], v[226:229], v[108:111]
	v_mfma_f32_16x16x32_bf16 v[92:95], v[138:141], v[234:237], v[92:95]
	v_mfma_f32_16x16x32_bf16 v[88:91], v[160:163], v[234:237], v[88:91]
	v_mfma_f32_16x16x32_bf16 v[76:79], v[138:141], v[242:245], v[76:79]
	v_mfma_f32_16x16x32_bf16 v[72:75], v[160:163], v[242:245], v[72:75]
	s_setprio 0
	s_setprio 1
	v_mfma_f32_16x16x32_bf16 v[120:123], v[164:167], v[180:183], v[120:123]
	v_mfma_f32_16x16x32_bf16 v[116:119], v[172:175], v[180:183], v[116:119]
	v_mfma_f32_16x16x32_bf16 v[102:105], v[164:167], v[204:207], v[104:107]
	v_mfma_f32_16x16x32_bf16 v[98:101], v[172:175], v[204:207], v[98:101]
	v_mfma_f32_16x16x32_bf16 v[84:87], v[164:167], v[230:233], v[84:87]
	v_mfma_f32_16x16x32_bf16 v[80:83], v[172:175], v[230:233], v[80:83]
	v_mfma_f32_16x16x32_bf16 v[68:71], v[164:167], v[238:241], v[68:71]
	v_mfma_f32_16x16x32_bf16 v[64:67], v[172:175], v[238:241], v[64:67]
	v_mfma_f32_16x16x32_bf16 v[120:123], v[168:171], v[198:201], v[120:123]
	v_mfma_f32_16x16x32_bf16 v[116:119], v[176:179], v[198:201], v[116:119]
	v_mfma_f32_16x16x32_bf16 v[104:107], v[168:171], v[226:229], v[102:105]
	v_mfma_f32_16x16x32_bf16 v[100:103], v[176:179], v[226:229], v[98:101]
	v_mfma_f32_16x16x32_bf16 v[84:87], v[168:171], v[234:237], v[84:87]
	v_mfma_f32_16x16x32_bf16 v[80:83], v[176:179], v[234:237], v[80:83]
	v_mfma_f32_16x16x32_bf16 v[68:71], v[168:171], v[242:245], v[68:71]
	v_mfma_f32_16x16x32_bf16 v[64:67], v[176:179], v[242:245], v[64:67]
	s_setprio 0
	s_barrier
; #define PG8_STAGE(bufoff, gbase, voff) do { _Pragma("unroll") for (int _i = 0; _i < 2; ++_i) \
;         __builtin_amdgcn_global_load_lds((const unsigned*)((const char*)(gbase) + (voff)[_i]), (LAS unsigned*)(lds + (bufoff) + ldsw + _i * 8192), 16, 0, 0); } while (0)
; #define PG8_LDA(dst, b, h) do { _Pragma("unroll") for (int m = 0; m < 4; ++m) _Pragma("unroll") for (int k = 0; k < 2; ++k) dst[m][k] = *(const LAS bf16x8*)(lds + PG8_SA(b, h) + aoff + m * 2048 + k * 1024); } while (0)
; #define PG8_MMA(ai, bj, At, Bt) do { __builtin_amdgcn_s_setprio(1); _Pragma("unroll") for (int m = 0; m < 4; ++m) _Pragma("unroll") for (int n = 0; n < 2; ++n) _Pragma("unroll") for (int k = 0; k < 2; ++k) \
;         acc[ai][bj][m][n] = __builtin_amdgcn_mfma_f32_16x16x32_bf16(Bt[n][k], At[m][k], acc[ai][bj][m][n], 0, 0, 0); __builtin_amdgcn_s_setprio(0); } while (0)
; #define PG8_WAIT_V(n) asm volatile("s_waitcnt vmcnt(" #n ")" ::: "memory")
; #define PG8_WAIT_L(n) asm volatile("s_waitcnt lgkmcnt(" #n ")" ::: "memory")
; #define PG8_BAR __builtin_amdgcn_s_barrier()
; #define PG8_SCHED __builtin_amdgcn_sched_barrier(0)
; __device__ __forceinline__ void gemm_phase(LAS unsigned char* lds, const LAS unsigned char* jt, const int K, const int n0, const int n1, const int G, const int c) {
;     ...
;             PG8_LDA(At, 1, 1); PG8_STAGE(PG8_SB(1, 0), b3, voffB); PG8_STAGE(PG8_SB(1, 1), b3 + hstep, voffB); PG8_STAGE(PG8_SA(1, 0), a3, voffA);
;             PG8_WAIT_V(8); PG8_WAIT_L(0); PG8_BAR; PG8_MMA(1, 0, At, B0); PG8_MMA(1, 1, At, B1); PG8_BAR; PG8_SCHED;
;         }
	s_add_i32 s12, s19, s44
	v_lshl_add_u64 v[98:99], v[146:147], 0, s[80:81]
	s_mov_b32 m0, s12
	ds_read_b128 v[180:183], v190 offset:49152
	ds_read_b128 v[198:201], v190 offset:50176
	ds_read_b128 v[204:207], v190 offset:51200
	ds_read_b128 v[226:229], v190 offset:52224
	ds_read_b128 v[230:233], v190 offset:53248
	ds_read_b128 v[234:237], v190 offset:54272
	ds_read_b128 v[238:241], v190 offset:55296
	ds_read_b128 v[242:245], v190 offset:56320
	global_load_lds_dwordx4 v[98:99], off
	v_lshl_add_u64 v[98:99], v[184:185], 0, s[80:81]
	s_add_i32 m0, s12, 0x2000
	s_add_i32 s12, s24, s44
	global_load_lds_dwordx4 v[98:99], off
	v_lshl_add_u64 v[98:99], v[192:193], 0, s[80:81]
	s_mov_b32 m0, s12
	s_nop 0
	global_load_lds_dwordx4 v[98:99], off
	v_lshl_add_u64 v[98:99], v[208:209], 0, s[80:81]
	s_add_i32 m0, s12, 0x2000
	s_nop 0
	global_load_lds_dwordx4 v[98:99], off
	v_lshl_add_u64 v[98:99], v[246:247], 0, s[80:81]
	s_mov_b32 m0, s52
	s_nop 0
	global_load_lds_dwordx4 v[98:99], off
	v_lshl_add_u64 v[98:99], v[248:249], 0, s[80:81]
	s_mov_b32 m0, s53
	s_nop 0
	global_load_lds_dwordx4 v[98:99], off
	s_waitcnt vmcnt(8)
	s_waitcnt lgkmcnt(0)
	s_barrier
	s_setprio 1
	s_waitcnt lgkmcnt(0)
	v_mfma_f32_16x16x32_bf16 v[60:63], v[134:137], v[180:183], v[60:63]
	v_mfma_f32_16x16x32_bf16 v[56:59], v[142:145], v[180:183], v[56:59]
	v_mfma_f32_16x16x32_bf16 v[44:47], v[134:137], v[204:207], v[44:47]
	v_mfma_f32_16x16x32_bf16 v[40:43], v[142:145], v[204:207], v[40:43]
	v_mfma_f32_16x16x32_bf16 v[28:31], v[134:137], v[230:233], v[28:31]
	v_mfma_f32_16x16x32_bf16 v[24:27], v[142:145], v[230:233], v[24:27]
	v_mfma_f32_16x16x32_bf16 v[12:15], v[134:137], v[238:241], v[12:15]
	v_mfma_f32_16x16x32_bf16 v[8:11], v[142:145], v[238:241], v[8:11]
	v_mfma_f32_16x16x32_bf16 v[60:63], v[138:141], v[198:201], v[60:63]
	v_mfma_f32_16x16x32_bf16 v[56:59], v[160:163], v[198:201], v[56:59]
	v_mfma_f32_16x16x32_bf16 v[44:47], v[138:141], v[226:229], v[44:47]
	v_mfma_f32_16x16x32_bf16 v[40:43], v[160:163], v[226:229], v[40:43]
	v_mfma_f32_16x16x32_bf16 v[28:31], v[138:141], v[234:237], v[28:31]
	v_mfma_f32_16x16x32_bf16 v[24:27], v[160:163], v[234:237], v[24:27]
	v_mfma_f32_16x16x32_bf16 v[12:15], v[138:141], v[242:245], v[12:15]
	v_mfma_f32_16x16x32_bf16 v[8:11], v[160:163], v[242:245], v[8:11]
	s_setprio 0
	s_setprio 1
	v_mfma_f32_16x16x32_bf16 v[52:55], v[164:167], v[180:183], v[52:55]
	v_mfma_f32_16x16x32_bf16 v[48:51], v[172:175], v[180:183], v[48:51]
	v_mfma_f32_16x16x32_bf16 v[36:39], v[164:167], v[204:207], v[36:39]
	v_mfma_f32_16x16x32_bf16 v[32:35], v[172:175], v[204:207], v[32:35]
	v_mfma_f32_16x16x32_bf16 v[20:23], v[164:167], v[230:233], v[20:23]
	v_mfma_f32_16x16x32_bf16 v[16:19], v[172:175], v[230:233], v[16:19]
	v_mfma_f32_16x16x32_bf16 v[4:7], v[164:167], v[238:241], v[4:7]
	v_mfma_f32_16x16x32_bf16 v[0:3], v[172:175], v[238:241], v[0:3]
	v_mfma_f32_16x16x32_bf16 v[52:55], v[168:171], v[198:201], v[52:55]
	v_mfma_f32_16x16x32_bf16 v[48:51], v[176:179], v[198:201], v[48:51]
	v_mfma_f32_16x16x32_bf16 v[36:39], v[168:171], v[226:229], v[36:39]
	v_mfma_f32_16x16x32_bf16 v[32:35], v[176:179], v[226:229], v[32:35]
	v_mfma_f32_16x16x32_bf16 v[20:23], v[168:171], v[234:237], v[20:23]
	v_mfma_f32_16x16x32_bf16 v[16:19], v[176:179], v[234:237], v[16:19]
	v_mfma_f32_16x16x32_bf16 v[4:7], v[168:171], v[242:245], v[4:7]
	v_mfma_f32_16x16x32_bf16 v[0:3], v[176:179], v[242:245], v[0:3]
	s_setprio 0
	s_barrier
	s_add_u32 s14, s14, 0x100
	s_addc_u32 s15, s15, 0
	s_add_u32 s0, s0, 0x100
	s_addc_u32 s1, s1, 0
	s_cmp_ge_i32 s18, s49
	s_mov_b32 s12, s18
	s_cbranch_scc0 .LBB0_295
	s_and_b64 vcc, exec, s[38:39]
	s_cbranch_vccz .LBB0_298
